# v24_attnb
# speedup vs baseline: 1.0065x; 1.0022x over previous
; #define LAS __attribute__((address_space(3)))
; __device__ __forceinline__ void phase_attn(const Params& p, int l, LAS unsigned char* lds, int bid, int G, int tid) {
;     ...
;                     const int qb = 2 * qh + blk; int ks0 = 16 * qb - 8; ks0 = ks0 < 0 ? 0 : ks0; ks0 = ks0 > 32 ? 32 : ks0;
;                     f32x4 St[2];
; #pragma unroll
;                     for (int nb = 0; nb < 2; ++nb) { f32x4 a0 = {0.f, 0.f, 0.f, 0.f};
; #pragma unroll
;                         for (int ks = 0; ks < 4; ++ks) { const bf16x8 kf = *(const LAS bf16x8*)(Kt + (ks0 + nb * 16 + fr) * 272 + (ks * 32 + g * 8) * 2);
;                             a0 = __builtin_amdgcn_mfma_f32_16x16x32_bf16(kf, Qf[blk][ks], a0, 0, 0, 0); }
;                         St[nb] = a0; }
;                     const int qc = qb * 16 + fr; int cs = qc - 8; cs = cs < 0 ? 0 : cs; cs = cs > 48 ? 48 : cs;
;                     float mt = -INFINITY;
; #pragma unroll
;                     for (int nb = 0; nb < 2; ++nb)
; #pragma unroll
;                         for (int j = 0; j < 4; ++j) { const int kc = ks0 + nb * 16 + g * 4 + j; const bool ok = (kc >= cs) && (kc < cs + 16);
;                             int dc = kc - qc; dc = dc < -15 ? -15 : dc; dc = dc > 15 ? 15 : dc;
;                             const float sv = ok ? St[nb][j] + rp[dc + 15] : -INFINITY; St[nb][j] = sv; mt = fmaxf(mt, sv); }
;                     mt = fmaxf(mt, __shfl_xor(mt, 16)); mt = fmaxf(mt, __shfl_xor(mt, 32));
;                     const float mnew = fmaxf(mrun[blk], mt), alpha = __expf(mrun[blk] - mnew);
;                     float psum = 0.f;
; #pragma unroll
;                     for (int nb = 0; nb < 2; ++nb)
; #pragma unroll
;                         for (int j = 0; j < 4; ++j) { const float pe = __expf(St[nb][j] - mnew); St[nb][j] = pe; psum += pe; }
;                     lrun[blk] = lrun[blk] * alpha + psum; mrun[blk] = mnew;
;                     u32x4 pv; pv.x = pk2(St[0][0], St[0][1]); pv.y = pk2(St[0][2], St[0][3]); pv.z = pk2(St[1][0], St[1][1]); pv.w = pk2(St[1][2], St[1][3]);
;                     const bf16x8 Pf = __builtin_bit_cast(bf16x8, pv);
; #pragma unroll
;                     for (int db = 0; db < 8; ++db) { const LAS unsigned char* vp = Vt + (db * 16 + fr) * 144 + (ks0 + g * 4) * 2;
;                         const u32x2 lo = *(const LAS u32x2*)(vp), hi = *(const LAS u32x2*)(vp + 32);
.LBB0_247:
	s_movk_i32 s45, 0x1400
	s_add_i32 s4, s18, s94
	v_cmp_ge_u32_e32 vcc, s4, v135
	v_cmp_lt_u32_e64 s[4:5], s4, v137
	s_and_b64 s[40:41], vcc, s[4:5]
	s_waitcnt lgkmcnt(0)
	s_barrier
	s_and_saveexec_b64 s[4:5], s[40:41]
	s_cbranch_execz .LBB0_244
	ds_read_b128 v[116:119], v209
	ds_read_b128 v[120:123], v209 offset:64
	ds_read_b128 v[212:215], v209 offset:4416
	s_waitcnt lgkmcnt(2)
	v_mfma_f32_16x16x32_bf16 v[116:119], v[116:119], v[4:7], 0
	s_waitcnt lgkmcnt(1)
	v_mfma_f32_16x16x32_bf16 v[116:119], v[120:123], v[8:11], v[116:119]
	ds_read_b128 v[120:123], v209 offset:128
	s_waitcnt lgkmcnt(0)
	v_mfma_f32_16x16x32_bf16 v[116:119], v[120:123], v[12:15], v[116:119]
	ds_read_b128 v[120:123], v209 offset:192
	s_waitcnt lgkmcnt(0)
	v_mfma_f32_16x16x32_bf16 v[116:119], v[120:123], v[16:19], v[116:119]
	ds_read_b128 v[120:123], v209 offset:4352
	s_waitcnt lgkmcnt(0)
	v_mfma_f32_16x16x32_bf16 v[120:123], v[120:123], v[4:7], 0
	v_mfma_f32_16x16x32_bf16 v[120:123], v[212:215], v[8:11], v[120:123]
	ds_read_b128 v[212:215], v209 offset:4480
	s_waitcnt lgkmcnt(0)
	v_mfma_f32_16x16x32_bf16 v[120:123], v[212:215], v[12:15], v[120:123]
	ds_read_b128 v[212:215], v209 offset:4544
	s_waitcnt lgkmcnt(0)
	v_mfma_f32_16x16x32_bf16 v[120:123], v[212:215], v[16:19], v[120:123]
	v_add_u32_e32 v234, v1, v174
	v_add_u32_e32 v235, v1, v175
	v_add_u32_e32 v236, v1, v176
	v_add_u32_e32 v237, v1, v177
	v_add_u32_e32 v238, v1, v195
	v_add_u32_e32 v239, v1, v196
	v_add_u32_e32 v240, v1, v197
	v_add_u32_e32 v241, v1, v198
	ds_read_b32 v234, v234 offset:36892
	ds_read_b32 v235, v235 offset:36892
	ds_read_b32 v236, v236 offset:36892
	ds_read_b32 v237, v237 offset:36892
	ds_read_b32 v238, v238 offset:36892
	ds_read_b32 v239, v239 offset:36892
	ds_read_b32 v240, v240 offset:36892
	ds_read_b32 v241, v241 offset:36892
	v_mov_b32_e32 v248, 0xff800000
	s_waitcnt lgkmcnt(0)
	v_add_f32_e32 v234, v116, v234
	v_add_f32_e32 v235, v117, v235
	v_add_f32_e32 v236, v118, v236
	v_add_f32_e32 v237, v119, v237
	v_add_f32_e32 v238, v120, v238
	v_add_f32_e32 v239, v121, v239
	v_add_f32_e32 v240, v122, v240
	v_add_f32_e32 v241, v123, v241
	v_cndmask_b32_e64 v214, v248, v234, s[8:9]
	v_cndmask_b32_e64 v215, v248, v235, s[10:11]
	v_cndmask_b32_e64 v224, v248, v236, s[12:13]
	v_cndmask_b32_e64 v116, v248, v237, s[24:25]
	v_cndmask_b32_e64 v118, v248, v238, s[26:27]
	v_cndmask_b32_e64 v117, v248, v239, s[28:29]
	v_cndmask_b32_e64 v120, v248, v240, s[30:31]
	v_cndmask_b32_e64 v119, v248, v241, s[34:35]
	v_mov_b32_e32 v213, 0xff800000
	v_max3_f32 v121, v214, v213, v215
	v_max3_f32 v121, v121, v224, v116
	v_max3_f32 v121, v121, v118, v117
	v_max3_f32 v121, v121, v120, v119
	ds_bpermute_b32 v122, v169, v121
	v_add_u32_e32 v220, v167, v144
	s_waitcnt lgkmcnt(0)
	v_max_f32_e32 v122, v122, v122
	v_max_f32_e32 v121, v121, v122
	ds_bpermute_b32 v122, v170, v121
	s_waitcnt lgkmcnt(0)
	v_max3_f32 v212, v142, v121, v122
	v_sub_f32_e32 v116, v116, v212
	v_sub_f32_e32 v122, v214, v212
	v_mul_f32_e32 v116, 0x3fb8aa3b, v116
	v_mul_f32_e32 v122, 0x3fb8aa3b, v122
	v_exp_f32_e32 v225, v116
	v_sub_f32_e32 v116, v118, v212
	v_exp_f32_e32 v214, v122
	v_sub_f32_e32 v122, v215, v212
	v_mul_f32_e32 v116, 0x3fb8aa3b, v116
	v_mul_f32_e32 v122, 0x3fb8aa3b, v122
	v_exp_f32_e32 v226, v116
	v_sub_f32_e32 v116, v117, v212
	v_sub_f32_e32 v121, v142, v212
	v_exp_f32_e32 v215, v122
	v_sub_f32_e32 v122, v224, v212
	v_mul_f32_e32 v116, 0x3fb8aa3b, v116
	v_mul_f32_e32 v121, 0x3fb8aa3b, v121
	v_mul_f32_e32 v122, 0x3fb8aa3b, v122
	v_exp_f32_e32 v227, v116
	v_sub_f32_e32 v116, v120, v212
	v_add_u32_e32 v120, 0x4000, v220
	v_exp_f32_e32 v224, v122
	v_exp_f32_e32 v142, v121
	ds_read2_b64 v[120:123], v120 offset0:128 offset1:132
	v_mul_f32_e32 v116, 0x3fb8aa3b, v116
	v_exp_f32_e32 v228, v116
	v_sub_f32_e32 v116, v119, v212
	v_mul_f32_e32 v116, 0x3fb8aa3b, v116
	v_pk_mul_f32 v[54:55], v[54:55], v[142:143] op_sel_hi:[1,0]
	v_pk_mul_f32 v[52:53], v[52:53], v[142:143] op_sel_hi:[1,0]
	v_exp_f32_e32 v229, v116
	v_cvt_pk_bf16_f32 v116, v214, v215
	v_cvt_pk_bf16_f32 v117, v224, v225
	v_cvt_pk_bf16_f32 v118, v226, v227
	v_cvt_pk_bf16_f32 v119, v228, v229
	v_pk_mul_f32 v[58:59], v[58:59], v[142:143] op_sel_hi:[1,0]
	s_waitcnt lgkmcnt(0)
; #define LAS __attribute__((address_space(3)))
; __device__ __forceinline__ void phase_attn(const Params& p, int l, LAS unsigned char* lds, int bid, int G, int tid) {
;     ...
;                     const int qb = 2 * qh + blk; int ks0 = 16 * qb - 8; ks0 = ks0 < 0 ? 0 : ks0; ks0 = ks0 > 32 ? 32 : ks0;
;                     f32x4 St[2];
; #pragma unroll
;                     for (int nb = 0; nb < 2; ++nb) { f32x4 a0 = {0.f, 0.f, 0.f, 0.f};
; #pragma unroll
;                         for (int ks = 0; ks < 4; ++ks) { const bf16x8 kf = *(const LAS bf16x8*)(Kt + (ks0 + nb * 16 + fr) * 272 + (ks * 32 + g * 8) * 2);
;                             a0 = __builtin_amdgcn_mfma_f32_16x16x32_bf16(kf, Qf[blk][ks], a0, 0, 0, 0); }
;                         St[nb] = a0; }
;                     const int qc = qb * 16 + fr; int cs = qc - 8; cs = cs < 0 ? 0 : cs; cs = cs > 48 ? 48 : cs;
;                     float mt = -INFINITY;
; #pragma unroll
;                     for (int nb = 0; nb < 2; ++nb)
; #pragma unroll
;                         for (int j = 0; j < 4; ++j) { const int kc = ks0 + nb * 16 + g * 4 + j; const bool ok = (kc >= cs) && (kc < cs + 16);
;                             int dc = kc - qc; dc = dc < -15 ? -15 : dc; dc = dc > 15 ? 15 : dc;
;                             const float sv = ok ? St[nb][j] + rp[dc + 15] : -INFINITY; St[nb][j] = sv; mt = fmaxf(mt, sv); }
;                     mt = fmaxf(mt, __shfl_xor(mt, 16)); mt = fmaxf(mt, __shfl_xor(mt, 32));
;                     const float mnew = fmaxf(mrun[blk], mt), alpha = __expf(mrun[blk] - mnew);
;                     float psum = 0.f;
; #pragma unroll
;                     for (int nb = 0; nb < 2; ++nb)
; #pragma unroll
;                         for (int j = 0; j < 4; ++j) { const float pe = __expf(St[nb][j] - mnew); St[nb][j] = pe; psum += pe; }
;                     lrun[blk] = lrun[blk] * alpha + psum; mrun[blk] = mnew;
;                     u32x4 pv; pv.x = pk2(St[0][0], St[0][1]); pv.y = pk2(St[0][2], St[0][3]); pv.z = pk2(St[1][0], St[1][1]); pv.w = pk2(St[1][2], St[1][3]);
;                     const bf16x8 Pf = __builtin_bit_cast(bf16x8, pv);
; #pragma unroll
;                     for (int db = 0; db < 8; ++db) { const LAS unsigned char* vp = Vt + (db * 16 + fr) * 144 + (ks0 + g * 4) * 2;
;                         const u32x2 lo = *(const LAS u32x2*)(vp), hi = *(const LAS u32x2*)(vp + 32);
	v_mfma_f32_16x16x32_bf16 v[52:55], v[120:123], v[116:119], v[52:55]
	v_add_u32_e32 v120, 0x4800, v220
	ds_read2_b64 v[120:123], v120 offset0:160 offset1:164
	v_pk_mul_f32 v[56:57], v[56:57], v[142:143] op_sel_hi:[1,0]
	v_pk_mul_f32 v[62:63], v[62:63], v[142:143] op_sel_hi:[1,0]
	v_pk_mul_f32 v[60:61], v[60:61], v[142:143] op_sel_hi:[1,0]
	s_waitcnt lgkmcnt(0)
	v_mfma_f32_16x16x32_bf16 v[56:59], v[120:123], v[116:119], v[56:59]
	v_add_u32_e32 v120, 0x5000, v220
	ds_read2_b64 v[120:123], v120 offset0:192 offset1:196
	v_pk_mul_f32 v[66:67], v[66:67], v[142:143] op_sel_hi:[1,0]
	s_waitcnt lgkmcnt(0)
	v_mfma_f32_16x16x32_bf16 v[60:63], v[120:123], v[116:119], v[60:63]
	v_add_u32_e32 v120, 0x5800, v220
	ds_read2_b64 v[120:123], v120 offset0:224 offset1:228
	v_pk_mul_f32 v[64:65], v[64:65], v[142:143] op_sel_hi:[1,0]
	v_pk_mul_f32 v[74:75], v[74:75], v[142:143] op_sel_hi:[1,0]
	v_pk_mul_f32 v[72:73], v[72:73], v[142:143] op_sel_hi:[1,0]
	s_waitcnt lgkmcnt(0)
	v_mfma_f32_16x16x32_bf16 v[64:67], v[120:123], v[116:119], v[64:67]
	v_add_u32_e32 v120, 0x6800, v220
	ds_read2_b64 v[120:123], v120 offset1:4
	v_pk_mul_f32 v[82:83], v[82:83], v[142:143] op_sel_hi:[1,0]
	s_waitcnt lgkmcnt(0)
	v_mfma_f32_16x16x32_bf16 v[72:75], v[120:123], v[116:119], v[72:75]
	v_add_u32_e32 v120, 0x7000, v220
	ds_read2_b64 v[120:123], v120 offset0:32 offset1:36
	v_pk_mul_f32 v[80:81], v[80:81], v[142:143] op_sel_hi:[1,0]
	v_pk_mul_f32 v[70:71], v[70:71], v[142:143] op_sel_hi:[1,0]
	v_pk_mul_f32 v[68:69], v[68:69], v[142:143] op_sel_hi:[1,0]
	s_waitcnt lgkmcnt(0)
	v_mfma_f32_16x16x32_bf16 v[80:83], v[120:123], v[116:119], v[80:83]
	v_add_u32_e32 v120, 0x7800, v220
	ds_read2_b64 v[120:123], v120 offset0:64 offset1:68
	v_pk_mul_f32 v[78:79], v[78:79], v[142:143] op_sel_hi:[1,0]
	s_waitcnt lgkmcnt(0)
	v_mfma_f32_16x16x32_bf16 v[68:71], v[120:123], v[116:119], v[68:71]
	v_add_u32_e32 v120, 0x8000, v220
	ds_read2_b64 v[120:123], v120 offset0:96 offset1:100
	v_pk_mul_f32 v[76:77], v[76:77], v[142:143] op_sel_hi:[1,0]
	v_add_u32_e32 v220, v166, v153
	ds_read_b128 v[230:233], v220 offset:4416
	s_waitcnt lgkmcnt(1)
	v_mfma_f32_16x16x32_bf16 v[76:79], v[120:123], v[116:119], v[76:79]
	ds_read_b128 v[116:119], v220
	ds_read_b128 v[120:123], v220 offset:64
	s_waitcnt lgkmcnt(1)
	v_mfma_f32_16x16x32_bf16 v[116:119], v[116:119], v[20:23], 0
	s_waitcnt lgkmcnt(0)
	v_mfma_f32_16x16x32_bf16 v[116:119], v[120:123], v[24:27], v[116:119]
	ds_read_b128 v[120:123], v220 offset:128
	s_waitcnt lgkmcnt(0)
	v_mfma_f32_16x16x32_bf16 v[116:119], v[120:123], v[28:31], v[116:119]
	ds_read_b128 v[120:123], v220 offset:192
	s_waitcnt lgkmcnt(0)
	v_mfma_f32_16x16x32_bf16 v[120:123], v[120:123], v[32:35], v[116:119]
	s_nop 4
	ds_read_b128 v[116:119], v220 offset:4352
	s_waitcnt lgkmcnt(0)
	v_mfma_f32_16x16x32_bf16 v[116:119], v[116:119], v[20:23], 0
	v_mfma_f32_16x16x32_bf16 v[116:119], v[230:233], v[24:27], v[116:119]
	ds_read_b128 v[230:233], v220 offset:4480
	s_waitcnt lgkmcnt(0)
	v_mfma_f32_16x16x32_bf16 v[116:119], v[230:233], v[28:31], v[116:119]
	ds_read_b128 v[230:233], v220 offset:4544
	s_waitcnt lgkmcnt(0)
	v_mfma_f32_16x16x32_bf16 v[116:119], v[230:233], v[32:35], v[116:119]
	v_add_u32_e32 v234, v1, v199
	v_add_u32_e32 v235, v1, v200
	v_add_u32_e32 v236, v1, v201
	v_add_u32_e32 v237, v1, v202
	v_add_u32_e32 v238, v1, v203
	v_add_u32_e32 v239, v1, v204
	v_add_u32_e32 v240, v1, v205
	v_add_u32_e32 v241, v1, v206
	ds_read_b32 v234, v234 offset:36892
	ds_read_b32 v235, v235 offset:36892
	ds_read_b32 v236, v236 offset:36892
	ds_read_b32 v237, v237 offset:36892
	ds_read_b32 v238, v238 offset:36892
	ds_read_b32 v239, v239 offset:36892
	ds_read_b32 v240, v240 offset:36892
	ds_read_b32 v241, v241 offset:36892
	v_mov_b32_e32 v248, 0xff800000
	s_waitcnt lgkmcnt(0)
	v_add_f32_e32 v234, v120, v234
	v_add_f32_e32 v235, v121, v235
	v_add_f32_e32 v236, v122, v236
	v_add_f32_e32 v237, v123, v237
	v_add_f32_e32 v238, v116, v238
	v_add_f32_e32 v239, v117, v239
	v_add_f32_e32 v240, v118, v240
	v_add_f32_e32 v241, v119, v241
	v_cndmask_b32_e64 v230, v248, v234, s[36:37]
	v_cndmask_b32_e64 v213, v248, v235, s[48:49]
	v_cndmask_b32_e64 v231, v248, v236, s[74:75]
	v_cndmask_b32_e64 v120, v248, v237, s[76:77]
	v_cndmask_b32_e64 v123, v248, v238, s[78:79]
	v_cndmask_b32_e64 v122, v248, v239, s[82:83]
	v_cndmask_b32_e64 v117, v248, v240, s[84:85]
	v_cndmask_b32_e64 v116, v248, v241, s[86:87]
	s_mov_b64 s[40:41], exec
	s_branch .LBB0_243
